# K-loop: address/M0 arithmetic of load segments 2,3,4,5,6,8 hoisted before the preceding barrier (into the MFMA segment's tail)
# baseline (speedup 1.0000x reference)
.Lk_body:
	s_add_i32 s44, s4, 2
	s_add_u32 s8, s6, 0x80
	s_addc_u32 s5, s7, 0
	s_add_i32 s45, 0, 0x10000
	v_add_u32_e32 v140, s45, v234
	ds_read_b128 v[128:131], v140
	ds_read_b128 v[132:135], v140 offset:1024
	ds_read_b128 v[136:139], v140 offset:2048
	ds_read_b128 v[140:143], v140 offset:3072
	s_cmp_eq_u32 s27, s4
	s_cselect_b32 s4, s90, s8
	s_cselect_b32 s5, s91, s5
	s_cselect_b32 s9, s93, s43
	s_cselect_b32 s8, s92, s42
	v_lshl_add_u64 v[214:215], s[6:7], 0, v[206:207]
	s_add_i32 m0, s74, 0xc000
	ds_read_b128 v[144:147], v235
	ds_read_b128 v[148:151], v235 offset:1024
	ds_read_b128 v[152:155], v235 offset:2048
	ds_read_b128 v[156:159], v235 offset:3072
	ds_read_b128 v[160:163], v235 offset:4096
	ds_read_b128 v[164:167], v235 offset:5120
	ds_read_b128 v[168:171], v235 offset:6144
	ds_read_b128 v[210:213], v235 offset:7168
	global_load_lds_dwordx4 v[214:215], off
	v_lshl_add_u64 v[214:215], s[6:7], 0, v[208:209]
	s_add_i32 m0, s74, 0xe000
	s_nop 0
	global_load_lds_dwordx4 v[214:215], off
	s_waitcnt lgkmcnt(8)
	s_barrier
	s_waitcnt lgkmcnt(0)
	s_waitcnt lgkmcnt(0)
	v_mfma_f32_16x16x32_bf16 v[108:111], v[128:131], v[144:147], v[108:111]
	v_mfma_f32_16x16x32_bf16 v[104:107], v[136:139], v[144:147], v[104:107]
	v_mfma_f32_16x16x32_bf16 v[92:95], v[128:131], v[152:155], v[92:95]
	v_mfma_f32_16x16x32_bf16 v[80:83], v[136:139], v[152:155], v[80:83]
	v_mfma_f32_16x16x32_bf16 v[68:71], v[128:131], v[160:163], v[68:71]
	v_mfma_f32_16x16x32_bf16 v[56:59], v[136:139], v[160:163], v[56:59]
	v_mfma_f32_16x16x32_bf16 v[44:47], v[128:131], v[168:171], v[44:47]
	v_mfma_f32_16x16x32_bf16 v[32:35], v[136:139], v[168:171], v[32:35]
	v_mfma_f32_16x16x32_bf16 v[108:111], v[132:135], v[148:151], v[108:111]
	v_mfma_f32_16x16x32_bf16 v[104:107], v[140:143], v[148:151], v[104:107]
	v_mfma_f32_16x16x32_bf16 v[92:95], v[132:135], v[156:159], v[92:95]
	v_mfma_f32_16x16x32_bf16 v[80:83], v[140:143], v[156:159], v[80:83]
	v_mfma_f32_16x16x32_bf16 v[68:71], v[132:135], v[164:167], v[68:71]
	v_mfma_f32_16x16x32_bf16 v[56:59], v[140:143], v[164:167], v[56:59]
	v_mfma_f32_16x16x32_bf16 v[44:47], v[132:135], v[210:213], v[44:47]
	v_mfma_f32_16x16x32_bf16 v[32:35], v[140:143], v[210:213], v[32:35]
	s_add_i32 s45, s45, s97
	v_add_u32_e32 v172, s3, v234
	v_lshl_add_u64 v[244:245], s[8:9], 0, v[184:185]
	v_lshl_add_u64 v[246:247], s[8:9], 0, v[188:189]
	s_mov_b32 m0, s45
	s_barrier
	ds_read_b128 v[214:217], v172
	ds_read_b128 v[218:221], v172 offset:1024
	ds_read_b128 v[236:239], v172 offset:2048
	ds_read_b128 v[240:243], v172 offset:3072
	global_load_lds_dwordx4 v[244:245], off
	s_add_i32 m0, s45, 0x2000
	s_nop 0
	global_load_lds_dwordx4 v[246:247], off
	s_barrier
	s_waitcnt lgkmcnt(0)
	s_waitcnt lgkmcnt(0)
	v_mfma_f32_16x16x32_bf16 v[124:127], v[214:217], v[144:147], v[124:127]
	v_mfma_f32_16x16x32_bf16 v[120:123], v[236:239], v[144:147], v[120:123]
	v_mfma_f32_16x16x32_bf16 v[116:119], v[214:217], v[152:155], v[116:119]
	v_mfma_f32_16x16x32_bf16 v[112:115], v[236:239], v[152:155], v[112:115]
	v_mfma_f32_16x16x32_bf16 v[100:103], v[214:217], v[160:163], v[100:103]
	v_mfma_f32_16x16x32_bf16 v[96:99], v[236:239], v[160:163], v[96:99]
	v_mfma_f32_16x16x32_bf16 v[76:79], v[214:217], v[168:171], v[76:79]
	v_mfma_f32_16x16x32_bf16 v[72:75], v[236:239], v[168:171], v[72:75]
	v_mfma_f32_16x16x32_bf16 v[124:127], v[218:221], v[148:151], v[124:127]
	v_mfma_f32_16x16x32_bf16 v[120:123], v[240:243], v[148:151], v[120:123]
	v_mfma_f32_16x16x32_bf16 v[116:119], v[218:221], v[156:159], v[116:119]
	v_mfma_f32_16x16x32_bf16 v[112:115], v[240:243], v[156:159], v[112:115]
	v_mfma_f32_16x16x32_bf16 v[100:103], v[218:221], v[164:167], v[100:103]
	v_mfma_f32_16x16x32_bf16 v[96:99], v[240:243], v[164:167], v[96:99]
	v_mfma_f32_16x16x32_bf16 v[76:79], v[218:221], v[210:213], v[76:79]
	v_mfma_f32_16x16x32_bf16 v[72:75], v[240:243], v[210:213], v[72:75]
	s_mov_b32 m0, s74
	v_lshl_add_u64 v[248:249], s[4:5], 0, v[182:183]
	v_lshl_add_u64 v[250:251], s[4:5], 0, v[186:187]
	s_barrier
	ds_read_b128 v[144:147], v235 offset:16384
	ds_read_b128 v[148:151], v235 offset:17408
	ds_read_b128 v[152:155], v235 offset:18432
	ds_read_b128 v[156:159], v235 offset:19456
	ds_read_b128 v[160:163], v235 offset:20480
	ds_read_b128 v[164:167], v235 offset:21504
	ds_read_b128 v[168:171], v235 offset:22528
	ds_read_b128 v[210:213], v235 offset:23552
	global_load_lds_dwordx4 v[248:249], off
	s_mov_b32 m0, s56
	s_nop 0
	global_load_lds_dwordx4 v[250:251], off
	s_barrier
	s_waitcnt lgkmcnt(0)
	s_waitcnt lgkmcnt(0)
	v_mfma_f32_16x16x32_bf16 v[52:55], v[128:131], v[144:147], v[52:55]
	v_mfma_f32_16x16x32_bf16 v[48:51], v[136:139], v[144:147], v[48:51]
	v_mfma_f32_16x16x32_bf16 v[28:31], v[128:131], v[152:155], v[28:31]
	v_mfma_f32_16x16x32_bf16 v[24:27], v[136:139], v[152:155], v[24:27]
	v_mfma_f32_16x16x32_bf16 v[12:15], v[128:131], v[160:163], v[12:15]
	v_mfma_f32_16x16x32_bf16 v[8:11], v[136:139], v[160:163], v[8:11]
	v_mfma_f32_16x16x32_bf16 v[4:7], v[128:131], v[168:171], v[4:7]
	v_mfma_f32_16x16x32_bf16 v[0:3], v[136:139], v[168:171], v[0:3]
	v_mfma_f32_16x16x32_bf16 v[52:55], v[132:135], v[148:151], v[52:55]
	v_mfma_f32_16x16x32_bf16 v[48:51], v[140:143], v[148:151], v[48:51]
	v_mfma_f32_16x16x32_bf16 v[28:31], v[132:135], v[156:159], v[28:31]
	v_mfma_f32_16x16x32_bf16 v[24:27], v[140:143], v[156:159], v[24:27]
	v_mfma_f32_16x16x32_bf16 v[12:15], v[132:135], v[164:167], v[12:15]
	v_mfma_f32_16x16x32_bf16 v[8:11], v[140:143], v[164:167], v[8:11]
	v_mfma_f32_16x16x32_bf16 v[4:7], v[132:135], v[210:213], v[4:7]
	v_mfma_f32_16x16x32_bf16 v[0:3], v[140:143], v[210:213], v[0:3]
	s_add_u32 s8, s8, s78
	s_addc_u32 s9, s9, 0
	s_add_i32 s45, s3, s97
	s_mov_b32 m0, s45
	v_lshl_add_u64 v[252:253], s[8:9], 0, v[184:185]
	v_lshl_add_u64 v[230:231], s[8:9], 0, v[188:189]
	s_barrier
	global_load_lds_dwordx4 v[252:253], off
	s_add_i32 m0, s45, 0x2000
	s_nop 0
	global_load_lds_dwordx4 v[230:231], off
	s_waitcnt vmcnt(6)
	s_barrier
	v_mfma_f32_16x16x32_bf16 v[88:91], v[214:217], v[144:147], v[88:91]
	v_mfma_f32_16x16x32_bf16 v[84:87], v[236:239], v[144:147], v[84:87]
	v_mfma_f32_16x16x32_bf16 v[64:67], v[214:217], v[152:155], v[64:67]
	v_mfma_f32_16x16x32_bf16 v[60:63], v[236:239], v[152:155], v[60:63]
	v_mfma_f32_16x16x32_bf16 v[40:43], v[214:217], v[160:163], v[40:43]
	v_mfma_f32_16x16x32_bf16 v[36:39], v[236:239], v[160:163], v[36:39]
	v_mfma_f32_16x16x32_bf16 v[20:23], v[214:217], v[168:171], v[20:23]
	v_mfma_f32_16x16x32_bf16 v[16:19], v[236:239], v[168:171], v[16:19]
	v_mfma_f32_16x16x32_bf16 v[88:91], v[218:221], v[148:151], v[88:91]
	v_mfma_f32_16x16x32_bf16 v[84:87], v[240:243], v[148:151], v[84:87]
	v_mfma_f32_16x16x32_bf16 v[64:67], v[218:221], v[156:159], v[64:67]
	v_mfma_f32_16x16x32_bf16 v[60:63], v[240:243], v[156:159], v[60:63]
	v_mfma_f32_16x16x32_bf16 v[40:43], v[218:221], v[164:167], v[40:43]
	v_mfma_f32_16x16x32_bf16 v[36:39], v[240:243], v[164:167], v[36:39]
	v_mfma_f32_16x16x32_bf16 v[20:23], v[218:221], v[210:213], v[20:23]
	v_mfma_f32_16x16x32_bf16 v[16:19], v[240:243], v[210:213], v[16:19]
	s_add_i32 s8, 0, 0x18000
	v_add_u32_e32 v140, s8, v234
	s_add_u32 s4, s4, s60
	s_addc_u32 s5, s5, 0
	v_lshl_add_u64 v[214:215], s[4:5], 0, v[182:183]
	v_lshl_add_u64 v[216:217], s[4:5], 0, v[186:187]
	s_mov_b32 m0, s57
	s_barrier
	ds_read_b128 v[128:131], v140
	ds_read_b128 v[132:135], v140 offset:1024
	ds_read_b128 v[136:139], v140 offset:2048
	ds_read_b128 v[140:143], v140 offset:3072
	ds_read_b128 v[144:147], v235 offset:32768
	ds_read_b128 v[148:151], v235 offset:33792
	ds_read_b128 v[152:155], v235 offset:34816
	ds_read_b128 v[156:159], v235 offset:35840
	ds_read_b128 v[160:163], v235 offset:36864
	ds_read_b128 v[164:167], v235 offset:37888
	ds_read_b128 v[168:171], v235 offset:38912
	ds_read_b128 v[210:213], v235 offset:39936
	global_load_lds_dwordx4 v[214:215], off
	s_mov_b32 m0, s68
	s_nop 0
	global_load_lds_dwordx4 v[216:217], off
	s_waitcnt lgkmcnt(8)
	s_barrier
	s_waitcnt lgkmcnt(0)
	s_waitcnt lgkmcnt(0)
	v_mfma_f32_16x16x32_bf16 v[108:111], v[128:131], v[144:147], v[108:111]
	v_mfma_f32_16x16x32_bf16 v[104:107], v[136:139], v[144:147], v[104:107]
	v_mfma_f32_16x16x32_bf16 v[92:95], v[128:131], v[152:155], v[92:95]
	v_mfma_f32_16x16x32_bf16 v[80:83], v[136:139], v[152:155], v[80:83]
	v_mfma_f32_16x16x32_bf16 v[68:71], v[128:131], v[160:163], v[68:71]
	v_mfma_f32_16x16x32_bf16 v[56:59], v[136:139], v[160:163], v[56:59]
	v_mfma_f32_16x16x32_bf16 v[44:47], v[128:131], v[168:171], v[44:47]
	v_mfma_f32_16x16x32_bf16 v[32:35], v[136:139], v[168:171], v[32:35]
	v_mfma_f32_16x16x32_bf16 v[108:111], v[132:135], v[148:151], v[108:111]
	v_mfma_f32_16x16x32_bf16 v[104:107], v[140:143], v[148:151], v[104:107]
	v_mfma_f32_16x16x32_bf16 v[92:95], v[132:135], v[156:159], v[92:95]
	v_mfma_f32_16x16x32_bf16 v[80:83], v[140:143], v[156:159], v[80:83]
	v_mfma_f32_16x16x32_bf16 v[68:71], v[132:135], v[164:167], v[68:71]
	v_mfma_f32_16x16x32_bf16 v[56:59], v[140:143], v[164:167], v[56:59]
	v_mfma_f32_16x16x32_bf16 v[44:47], v[132:135], v[210:213], v[44:47]
	v_mfma_f32_16x16x32_bf16 v[32:35], v[140:143], v[210:213], v[32:35]
	s_add_i32 s4, 0, 0x1c000
	s_add_i32 s5, s8, s97
	v_add_u32_e32 v172, s4, v234
	v_lshl_add_u64 v[244:245], v[244:245], 0, s[54:55]
	s_mov_b32 m0, s5
	s_barrier
	ds_read_b128 v[214:217], v172
	ds_read_b128 v[218:221], v172 offset:1024
	ds_read_b128 v[236:239], v172 offset:2048
	ds_read_b128 v[240:243], v172 offset:3072
	global_load_lds_dwordx4 v[244:245], off
	v_lshl_add_u64 v[244:245], v[246:247], 0, s[54:55]
	s_add_i32 m0, s5, 0x2000
	s_nop 0
	global_load_lds_dwordx4 v[244:245], off
	s_barrier
	s_waitcnt lgkmcnt(0)
	s_waitcnt lgkmcnt(0)
	v_mfma_f32_16x16x32_bf16 v[124:127], v[214:217], v[144:147], v[124:127]
	v_mfma_f32_16x16x32_bf16 v[120:123], v[236:239], v[144:147], v[120:123]
	v_mfma_f32_16x16x32_bf16 v[116:119], v[214:217], v[152:155], v[116:119]
	v_mfma_f32_16x16x32_bf16 v[112:115], v[236:239], v[152:155], v[112:115]
	v_mfma_f32_16x16x32_bf16 v[100:103], v[214:217], v[160:163], v[100:103]
	v_mfma_f32_16x16x32_bf16 v[96:99], v[236:239], v[160:163], v[96:99]
	v_mfma_f32_16x16x32_bf16 v[76:79], v[214:217], v[168:171], v[76:79]
	v_mfma_f32_16x16x32_bf16 v[72:75], v[236:239], v[168:171], v[72:75]
	v_mfma_f32_16x16x32_bf16 v[124:127], v[218:221], v[148:151], v[124:127]
	v_mfma_f32_16x16x32_bf16 v[120:123], v[240:243], v[148:151], v[120:123]
	v_mfma_f32_16x16x32_bf16 v[116:119], v[218:221], v[156:159], v[116:119]
	v_mfma_f32_16x16x32_bf16 v[112:115], v[240:243], v[156:159], v[112:115]
	v_mfma_f32_16x16x32_bf16 v[100:103], v[218:221], v[164:167], v[100:103]
	v_mfma_f32_16x16x32_bf16 v[96:99], v[240:243], v[164:167], v[96:99]
	v_mfma_f32_16x16x32_bf16 v[76:79], v[218:221], v[210:213], v[76:79]
	v_mfma_f32_16x16x32_bf16 v[72:75], v[240:243], v[210:213], v[72:75]
	s_mov_b32 m0, s69
	v_lshl_add_u64 v[244:245], v[248:249], 0, s[54:55]
	s_barrier
	ds_read_b128 v[144:147], v235 offset:49152
	ds_read_b128 v[148:151], v235 offset:50176
	ds_read_b128 v[152:155], v235 offset:51200
	ds_read_b128 v[156:159], v235 offset:52224
	ds_read_b128 v[160:163], v235 offset:53248
	ds_read_b128 v[164:167], v235 offset:54272
	ds_read_b128 v[168:171], v235 offset:55296
	ds_read_b128 v[210:213], v235 offset:56320
	global_load_lds_dwordx4 v[244:245], off
	v_lshl_add_u64 v[244:245], v[250:251], 0, s[54:55]
	s_mov_b32 m0, s26
	s_nop 0
	global_load_lds_dwordx4 v[244:245], off
	s_barrier
	s_waitcnt lgkmcnt(0)
	s_waitcnt lgkmcnt(0)
	v_mfma_f32_16x16x32_bf16 v[52:55], v[128:131], v[144:147], v[52:55]
	v_mfma_f32_16x16x32_bf16 v[48:51], v[136:139], v[144:147], v[48:51]
	v_mfma_f32_16x16x32_bf16 v[28:31], v[128:131], v[152:155], v[28:31]
	v_mfma_f32_16x16x32_bf16 v[24:27], v[136:139], v[152:155], v[24:27]
	v_mfma_f32_16x16x32_bf16 v[12:15], v[128:131], v[160:163], v[12:15]
	v_mfma_f32_16x16x32_bf16 v[8:11], v[136:139], v[160:163], v[8:11]
	v_mfma_f32_16x16x32_bf16 v[4:7], v[128:131], v[168:171], v[4:7]
	v_mfma_f32_16x16x32_bf16 v[0:3], v[136:139], v[168:171], v[0:3]
	v_mfma_f32_16x16x32_bf16 v[52:55], v[132:135], v[148:151], v[52:55]
	v_mfma_f32_16x16x32_bf16 v[48:51], v[140:143], v[148:151], v[48:51]
	v_mfma_f32_16x16x32_bf16 v[28:31], v[132:135], v[156:159], v[28:31]
	v_mfma_f32_16x16x32_bf16 v[24:27], v[140:143], v[156:159], v[24:27]
	v_mfma_f32_16x16x32_bf16 v[12:15], v[132:135], v[164:167], v[12:15]
	v_mfma_f32_16x16x32_bf16 v[8:11], v[140:143], v[164:167], v[8:11]
	v_mfma_f32_16x16x32_bf16 v[4:7], v[132:135], v[210:213], v[4:7]
	v_mfma_f32_16x16x32_bf16 v[0:3], v[140:143], v[210:213], v[0:3]
	s_add_i32 s4, s4, s97
	s_mov_b32 m0, s4
	v_lshl_add_u64 v[128:129], v[252:253], 0, s[54:55]
	v_lshl_add_u64 v[130:131], v[230:231], 0, s[54:55]
	s_barrier
	global_load_lds_dwordx4 v[128:129], off
	s_add_i32 m0, s4, 0x2000
	s_nop 0
	global_load_lds_dwordx4 v[130:131], off
	s_waitcnt vmcnt(6)
	s_barrier
	v_mfma_f32_16x16x32_bf16 v[88:91], v[214:217], v[144:147], v[88:91]
	v_mfma_f32_16x16x32_bf16 v[84:87], v[236:239], v[144:147], v[84:87]
	v_mfma_f32_16x16x32_bf16 v[64:67], v[214:217], v[152:155], v[64:67]
	v_mfma_f32_16x16x32_bf16 v[60:63], v[236:239], v[152:155], v[60:63]
	v_mfma_f32_16x16x32_bf16 v[40:43], v[214:217], v[160:163], v[40:43]
	v_mfma_f32_16x16x32_bf16 v[36:39], v[236:239], v[160:163], v[36:39]
	v_mfma_f32_16x16x32_bf16 v[20:23], v[214:217], v[168:171], v[20:23]
	v_mfma_f32_16x16x32_bf16 v[16:19], v[236:239], v[168:171], v[16:19]
	v_mfma_f32_16x16x32_bf16 v[88:91], v[218:221], v[148:151], v[88:91]
	v_mfma_f32_16x16x32_bf16 v[84:87], v[240:243], v[148:151], v[84:87]
	v_mfma_f32_16x16x32_bf16 v[64:67], v[218:221], v[156:159], v[64:67]
	v_mfma_f32_16x16x32_bf16 v[60:63], v[240:243], v[156:159], v[60:63]
	v_mfma_f32_16x16x32_bf16 v[40:43], v[218:221], v[164:167], v[40:43]
	v_mfma_f32_16x16x32_bf16 v[36:39], v[240:243], v[164:167], v[36:39]
	v_mfma_f32_16x16x32_bf16 v[20:23], v[218:221], v[210:213], v[20:23]
	v_mfma_f32_16x16x32_bf16 v[16:19], v[240:243], v[210:213], v[16:19]
	s_add_u32 s6, s6, 0x100
	s_addc_u32 s7, s7, 0
	s_add_u32 s42, s42, 0x100
	s_addc_u32 s43, s43, 0
	s_cmp_ge_u32 s44, s73
	s_mov_b32 s4, s44
	s_cbranch_scc0 .LBB0_744
	s_barrier
	s_nop 0
	s_lshl_b32 s52, s30, 8
	s_cmp_lt_i32 s96, 2
	s_mov_b64 s[4:5], -1
	s_cbranch_scc1 .LBB0_898
	s_cmp_gt_i32 s96, 2
	s_cbranch_scc0 .LBB0_895
	s_add_i32 s30, s52, s82
	v_or_b32_e32 v210, s30, v179
	s_and_b32 s4, s10, -4
	s_cmp_lg_u32 s4, 4
	s_movk_i32 s4, 0x2000
	s_movk_i32 s6, 0x1fff
	v_or_b32_e32 v212, 16, v210
	v_cmp_gt_i32_e32 vcc, s4, v210
	v_cmp_lt_i32_e64 s[42:43], s6, v210
	s_mov_b64 s[4:5], -1
	v_ashrrev_i32_e32 v211, 31, v210
	s_movk_i32 s53, 0x1fff
	v_cmp_lt_i32_e64 s[46:47], s6, v212
	s_cbranch_scc0 .LBB0_829
	v_lshlrev_b32_e32 v128, 6, v212
	s_movk_i32 s4, 0x2000
	v_and_b32_e32 v128, 0x3f7c0, v128
	v_cmp_gt_i32_e64 s[44:45], s4, v212
	v_lshlrev_b32_e32 v219, 6, v210
	v_and_b32_e32 v144, 0x3f3c0, v219
	v_cndmask_b32_e64 v128, v225, v128, s[44:45]
	v_lshlrev_b32_e32 v172, 2, v128
	v_cndmask_b32_e32 v144, v225, v144, vcc
	v_lshl_add_u64 v[132:133], v[196:197], 0, v[172:173]
	v_lshl_add_u64 v[140:141], v[198:199], 0, v[172:173]
	v_lshlrev_b32_e32 v172, 2, v144
	v_lshl_add_u64 v[144:145], v[198:199], 0, v[172:173]
	global_load_dwordx4 v[128:131], v[132:133], off offset:16
	global_load_dwordx4 v[136:139], v[132:133], off
	s_nop 0
	global_load_dwordx4 v[132:135], v[140:141], off offset:16
	s_nop 0
	global_load_dwordx4 v[140:143], v[140:141], off
	s_nop 0
	global_load_dwordx4 v[156:159], v[144:145], off offset:16
	global_load_dwordx4 v[152:155], v[144:145], off
	v_lshl_add_u64 v[144:145], v[196:197], 0, v[172:173]
	global_load_dwordx4 v[160:163], v[144:145], off offset:16
	global_load_dwordx4 v[164:167], v[144:145], off
	s_cmp_gt_i32 s10, 3
	s_cselect_b64 s[4:5], -1, 0
	s_lshl_b32 s6, s10, 1
	s_add_i32 s7, s6, -16
	s_cmp_lt_i32 s10, 4
	s_cselect_b32 s6, s6, s7
	v_readlane_b32 s7, v255, 50
	s_or_b32 s6, s6, s7
	s_lshl_b32 s94, s6, 7
	s_ashr_i32 s95, s94, 31
	s_lshl_b64 s[6:7], s[94:95], 1
	v_lshl_add_u64 v[214:215], v[200:201], 0, s[6:7]
	s_waitcnt vmcnt(0)
	v_pk_mul_f32 v[144:145], v[126:127], v[154:155]
	v_pk_mul_f32 v[148:149], v[124:125], v[152:153]
	v_pk_fma_f32 v[146:147], v[110:111], v[166:167], v[144:145] neg_lo:[0,0,1] neg_hi:[0,0,1]
	v_pk_fma_f32 v[144:145], v[108:109], v[164:165], v[148:149] neg_lo:[0,0,1] neg_hi:[0,0,1]
	v_pk_mul_f32 v[148:149], v[122:123], v[158:159]
	v_pk_mul_f32 v[168:169], v[120:121], v[156:157]
	v_pk_fma_f32 v[150:151], v[106:107], v[162:163], v[148:149] neg_lo:[0,0,1] neg_hi:[0,0,1]
	v_pk_fma_f32 v[148:149], v[104:105], v[160:161], v[168:169] neg_lo:[0,0,1] neg_hi:[0,0,1]
	v_pk_mul_f32 v[166:167], v[126:127], v[166:167]
	v_pk_mul_f32 v[164:165], v[124:125], v[164:165]
	v_pk_mul_f32 v[162:163], v[122:123], v[162:163]
	v_pk_mul_f32 v[160:161], v[120:121], v[160:161]
	v_pk_fma_f32 v[154:155], v[110:111], v[154:155], v[166:167]
	v_pk_fma_f32 v[152:153], v[108:109], v[152:153], v[164:165]
	v_pk_fma_f32 v[158:159], v[106:107], v[158:159], v[162:163]
	v_pk_fma_f32 v[156:157], v[104:105], v[156:157], v[160:161]
	v_cvt_pk_bf16_f32 v160, v144, v145
	v_cvt_pk_bf16_f32 v161, v146, v147
	v_cvt_pk_bf16_f32 v162, v148, v149
	v_cvt_pk_bf16_f32 v163, v150, v151
	v_cvt_pk_bf16_f32 v164, v152, v153
	v_cvt_pk_bf16_f32 v165, v154, v155
	v_cvt_pk_bf16_f32 v166, v156, v157
	v_cvt_pk_bf16_f32 v167, v158, v159
	s_mov_b64 s[8:9], -1
	s_and_b64 vcc, exec, s[4:5]
	s_cbranch_vccz .LBB0_750
	s_movk_i32 s8, 0x1800
	v_mad_i64_i32 v[168:169], s[8:9], v210, s8, v[214:215]
	global_store_dwordx4 v[168:169], v[160:163], off
	global_store_dwordx4 v[168:169], v[164:167], off offset:128
	s_mov_b64 s[8:9], 0
